# speedup vs baseline: 1.0215x; 1.0060x over previous
; DEV int ltid() { int t = threadIdx.x; asm volatile("" : "+v"(t)); return t; }
; DEV int v_st(int k, int c) { const int kk = (k & ~0xC) | ((k & 4) << 1) | ((k & 8) >> 1); return ((kk >> 3) * 4 + (c >> 5)) * 512 + ((kk & 7) * 32 + (c & 31)) * 2; }
; DEV int v_rd_base(int lane) { return ((lane & 3) << 3) | (((lane >> 2) & 3) << 6) | (((lane >> 4) & 1) << 5) | (((lane >> 5) & 1) << 8); }
; #define SLOAD(i, k0) do { sr_[i].vs0 = LD8(&Vh[(long)((k0) + sr) * LDK + sc]); sr_[i].vs1 = LD8(&Vh[(long)((k0) + 32 + sr) * LDK + sc]); \
;     sr_[i].ks0 = LD8(&Kh[(long)((k0) + sr) * LDK + sc]); sr_[i].ks1 = LD8(&Kh[(long)((k0) + 32 + sr) * LDK + sc]); \
;     sr_[i].kp = LD8(&KPh[(long)((k0) + pr) * LDKP + pc]); } while (0)
; DEV void attn_item(const u16* __restrict__ Qb, const u16* __restrict__ Kh, const u16* __restrict__ Vh, const u16* __restrict__ KPh,
;                    u16* __restrict__ Ob, int seq, char* lds) {
;   const int tid = ltid(), wid = tid >> 6, lane = tid & 63, r32 = lane & 31, hi = lane >> 5;
;   char* V_lds = lds; char* K_lds = lds + 2 * SHM_V; char* KP_lds = lds + 2 * SHM_V + 2 * SHM_K;
;   float* wsf = (float*)(lds + 2 * SHM_V + 2 * SHM_K + 2 * SHM_KP) + wid * 64; float* li_l = wsf; float* al_l = wsf + 32;
;   char* qpl = lds + 2 * SHM_V + 2 * SHM_K + 2 * SHM_KP + 2048 + wid * ((12 - NQR) * 1024) + lane * 16;
;   float m_reg = -1e30f, l_reg = 0; f32x16 o[4] = {}; bf16x8 qr[NQR];
;   const u16* Qw = Qb + (long)(wid * QBLK + r32) * LDQ + hi * 8;
; #pragma unroll
;   for (int d0 = 0; d0 < NQR; ++d0) qr[d0] = *reinterpret_cast<const bf16x8*>(Qw + d0 * 16);
; #pragma unroll
;   for (int d1 = NQR; d1 < 12; ++d1) *reinterpret_cast<bf16x8*>(qpl + (d1 - NQR) * 1024) = *reinterpret_cast<const bf16x8*>(Qw + d1 * 16);
;   const int sr = tid >> 4, sc = (tid & 15) * 8, vst0 = v_st(sr, sc), vst1 = v_st(32 + sr, sc);
;   const int pr = tid >> 3, pc = (tid & 7) * 8, kpst = KPSWZ(pr, pc * 2);
;   const int vb0 = (int)(uintptr_t)V_lds + v_rd_base(lane);
;   struct { bf16x8 vs0, vs1, ks0, ks1, kp; } sr_[1];
;     ...
;   f32x16 pA0, pA1, pB0, pB1; float mnA, mnB, alA, alB; bf16x8 pa0, pa1, pa2, pa3; const int NT = seq / KVBLK;
;   constexpr int SE = 0, SO = 0;
;   SLOAD(SE, 0); asm volatile("s_waitcnt vmcnt(0)" ::: "memory"); SWRITE(0, SE); __syncthreads();
.LBB0_303:
	s_mul_i32 s1, s35, 0x1800
	s_mul_hi_u32 s4, s34, 0x1800
	s_add_i32 s4, s4, s1
	s_mul_i32 s1, s34, 0x1800
	s_add_u32 s1, s20, s1
	s_mul_i32 s28, s0, 0xc0
	s_addc_u32 s7, s21, s4
	s_lshl_b64 s[4:5], s[28:29], 1
	s_add_u32 s6, s1, s4
	s_addc_u32 s7, s7, s5
	s_lshl_b64 s[4:5], s[54:55], 13
	v_mov_b32_e32 v50, v164
	s_barrier
	s_add_u32 s1, s24, s4
	s_addc_u32 s5, s25, s5
	v_ashrrev_i32_e32 v51, 6, v50
	s_lshl_b32 s28, s0, 8
	v_and_b32_e32 v148, 31, v50
	v_lshlrev_b32_e32 v138, 5, v51
	s_lshl_b64 s[62:63], s[28:29], 1
	v_bfe_u32 v149, v50, 5, 1
	v_or_b32_e32 v2, v138, v148
	v_mov_b64_e32 v[0:1], s[6:7]
	s_movk_i32 s0, 0x1800
	s_add_u32 s4, s1, s62
	v_mad_i64_i32 v[0:1], s[0:1], v2, s0, v[0:1]
	v_lshlrev_b32_e32 v136, 4, v149
	v_lshl_add_u64 v[46:47], v[0:1], 0, v[136:137]
	global_load_dwordx4 v[6:9], v[46:47], off offset:128
	global_load_dwordx4 v[10:13], v[46:47], off offset:160
	global_load_dwordx4 v[14:17], v[46:47], off offset:192
	global_load_dwordx4 v[18:21], v[46:47], off offset:224
	global_load_dwordx4 v[22:25], v[46:47], off offset:256
	global_load_dwordx4 v[26:29], v[46:47], off offset:288
	global_load_dwordx4 v[30:33], v[46:47], off offset:320
	global_load_dwordx4 v[34:37], v[46:47], off offset:352
	v_ashrrev_i32_e32 v48, 4, v50
	v_lshlrev_b32_e32 v66, 3, v50
	v_add_u32_e32 v64, 32, v48
	s_mul_i32 s0, s55, 0x880
	s_mul_hi_u32 s1, s54, 0x880
	v_and_b32_e32 v0, 0x78, v66
	v_ashrrev_i32_e32 v49, 31, v48
	v_ashrrev_i32_e32 v65, 31, v64
	s_addc_u32 s5, s5, s63
	s_add_i32 s1, s1, s0
	s_mul_i32 s6, s54, 0x880
	v_lshlrev_b32_e32 v67, 1, v0
	v_lshlrev_b64 v[2:3], 13, v[48:49]
	v_lshlrev_b64 v[4:5], 13, v[64:65]
	s_add_u32 s6, s22, s6
	v_or_b32_e32 v2, v2, v67
	v_or_b32_e32 v4, v4, v67
	s_addc_u32 s7, s23, s1
	v_lshl_add_u64 v[2:3], s[4:5], 0, v[2:3]
	v_lshl_add_u64 v[4:5], s[4:5], 0, v[4:5]
	v_ashrrev_i32_e32 v76, 3, v50
	v_lshlrev_b32_e32 v0, 4, v50
	global_load_dwordx4 v[38:41], v[2:3], off offset:256
	global_load_dwordx4 v[42:45], v[4:5], off offset:256
	global_load_dwordx4 v[52:55], v[2:3], off
	global_load_dwordx4 v[56:59], v[4:5], off
	v_mov_b64_e32 v[4:5], s[6:7]
	v_and_b32_e32 v0, 0x70, v0
	v_mad_i64_i32 v[60:61], s[4:5], v76, s71, v[4:5]
	v_mov_b32_e32 v1, v137
	v_lshl_add_u64 v[60:61], v[60:61], 0, v[0:1]
	global_load_dwordx4 v[60:63], v[60:61], off offset:2048
	s_nop 0
	global_load_dwordx4 v[108:111], v[46:47], off
	global_load_dwordx4 v[104:107], v[46:47], off offset:32
	global_load_dwordx4 v[100:103], v[46:47], off offset:64
	global_load_dwordx4 v[96:99], v[46:47], off offset:96
	v_and_b32_e32 v82, 63, v50
	v_lshlrev_b32_e32 v83, 4, v82
	v_lshl_add_u32 v51, v51, 13, v145
	v_and_b32_e32 v65, 0xfffff0, v48
	v_lshlrev_b32_e32 v68, 1, v48
	v_or_b32_e32 v77, v51, v83
	v_or_b32_e32 v78, 64, v136
	v_or_b32_e32 v79, 0x60, v136
	v_and_b32_e32 v85, 0x70, v66
	s_mov_b64 s[4:5], 0x80000
	v_and_b32_e32 v80, 0x3fffffc0, v50
	v_lshl_add_u32 v139, v80, 2, v144
	s_mov_b32 s6, s29
	s_mov_b32 s7, s29
	s_mov_b32 s8, s29
	s_mov_b32 s9, s29
	s_mov_b32 s10, s29
	s_mov_b32 s11, s29
	s_mov_b32 s12, s29
	s_mov_b32 s13, s29
	s_mov_b32 s14, s29
	s_mov_b32 s15, s29
	s_mov_b32 s16, s29
	s_mov_b32 s17, s29
	s_mov_b32 s18, s29
	s_waitcnt vmcnt(16)
	ds_write_b128 v77, v[6:9]
	s_waitcnt vmcnt(15)
	ds_write_b128 v77, v[10:13] offset:1024
	s_waitcnt vmcnt(14)
	ds_write_b128 v77, v[14:17] offset:2048
	s_waitcnt vmcnt(13)
	ds_write_b128 v77, v[18:21] offset:3072
	s_waitcnt vmcnt(12)
	ds_write_b128 v77, v[22:25] offset:4096
	s_waitcnt vmcnt(11)
	ds_write_b128 v77, v[26:29] offset:5120
	s_waitcnt vmcnt(10)
	ds_write_b128 v77, v[30:33] offset:6144
	s_waitcnt vmcnt(9)
	ds_write_b128 v77, v[34:37] offset:7168
	v_and_or_b32 v6, v68, 8, v65
	v_lshrrev_b32_e32 v7, 1, v48
	v_lshrrev_b32_e32 v6, 1, v6
	v_bfe_u32 v8, v66, 5, 2
	v_and_b32_e32 v9, 3, v48
	v_or_b32_e32 v6, v6, v8
	v_and_or_b32 v7, v7, 4, v9
	v_lshlrev_b32_e32 v6, 9, v6
	v_lshlrev_b32_e32 v7, 6, v7
	v_and_b32_e32 v9, 48, v67
	v_or3_b32 v154, v6, v7, v9
	v_and_b32_e32 v6, 0xfffff0, v64
	v_lshlrev_b32_e32 v10, 1, v64
	v_and_or_b32 v6, v10, 8, v6
	v_lshrrev_b32_e32 v6, 1, v6
	v_or_b32_e32 v6, v6, v8
	v_lshlrev_b32_e32 v6, 9, v6
	v_or3_b32 v155, v6, v7, v9
	v_lshlrev_b32_e32 v6, 7, v76
	v_and_b32_e32 v7, 0x70, v50
	v_bitop3_b32 v84, v0, v6, v7 bitop3:0xde
	v_lshlrev_b32_e32 v6, 8, v48
	v_and_b32_e32 v224, 0xf0, v50
	v_lshlrev_b32_e32 v225, 4, v50
	v_bitop3_b32 v156, v67, v6, v224 bitop3:0xde
	v_lshlrev_b32_e32 v6, 8, v64
	v_lshlrev_b32_e32 v14, 8, v148
	v_and_b32_e32 v225, 0xf0, v225
	v_bitop3_b32 v157, v67, v6, v224 bitop3:0xde
	v_add_u32_e32 v158, 0x10000, v84
	v_bitop3_b32 v159, v136, v14, v225 bitop3:0xde
	s_waitcnt vmcnt(0)
	s_waitcnt vmcnt(8)
	ds_write_b128 v154, v[38:41]
	s_waitcnt vmcnt(7)
	ds_write_b128 v155, v[42:45]
	s_waitcnt vmcnt(6)
	ds_write_b128 v156, v[52:55] offset:32768
	s_waitcnt vmcnt(5)
	ds_write_b128 v157, v[56:59] offset:32768
	s_waitcnt vmcnt(4)
	ds_write_b128 v158, v[60:63]
	s_waitcnt lgkmcnt(0)
	s_barrier
; #define SLOAD(i, k0) do { sr_[i].vs0 = LD8(&Vh[(long)((k0) + sr) * LDK + sc]); sr_[i].vs1 = LD8(&Vh[(long)((k0) + 32 + sr) * LDK + sc]); \
;     sr_[i].ks0 = LD8(&Kh[(long)((k0) + sr) * LDK + sc]); sr_[i].ks1 = LD8(&Kh[(long)((k0) + 32 + sr) * LDK + sc]); \
;     sr_[i].kp = LD8(&KPh[(long)((k0) + pr) * LDKP + pc]); } while (0)
; #define SWAIT() asm volatile("s_waitcnt vmcnt(0)" ::: "memory")
; DEV void qkt(f32x16& p0, f32x16& p1, const char* Ks, const char* KPs, const bf16x8* qr, const char* qpl, int r32, int hi) {
;   p0 = f32x16{}; p1 = f32x16{};
; #pragma unroll
;   for (int d0 = 0; d0 < 8; ++d0) { int cb = (d0 * 16 + hi * 8) * 2;
;     bf16x8 b0 = *reinterpret_cast<const bf16x8*>(Ks + KSWZ(r32, cb));
;     bf16x8 b1 = *reinterpret_cast<const bf16x8*>(Ks + KSWZ(32 + r32, cb));
;     bf16x8 qq = d0 < NQR ? qr[d0 < NQR ? d0 : 0] : *reinterpret_cast<const bf16x8*>(qpl + (d0 - NQR) * 1024);
;     p0 = __builtin_amdgcn_mfma_f32_32x32x16_bf16(b0, qq, p0, 0, 0, 0);
;     p1 = __builtin_amdgcn_mfma_f32_32x32x16_bf16(b1, qq, p1, 0, 0, 0); }
; #pragma unroll
;   for (int d1 = 0; d1 < 4; ++d1) { int cb = (d1 * 16 + hi * 8) * 2;
;     bf16x8 b0 = *reinterpret_cast<const bf16x8*>(KPs + KPSWZ(r32, cb));
;     bf16x8 b1 = *reinterpret_cast<const bf16x8*>(KPs + KPSWZ(32 + r32, cb));
;     bf16x8 qp = *reinterpret_cast<const bf16x8*>(qpl + (8 - NQR + d1) * 1024);
;     p0 = __builtin_amdgcn_mfma_f32_32x32x16_bf16(b0, qp, p0, 0, 0, 0);
;     p1 = __builtin_amdgcn_mfma_f32_32x32x16_bf16(b1, qp, p1, 0, 0, 0); }
; DEV void attn_item(const u16* __restrict__ Qb, const u16* __restrict__ Kh, const u16* __restrict__ Vh, const u16* __restrict__ KPh,
;                    u16* __restrict__ Ob, int seq, char* lds) {
;     ...
;   qkt(pA0, pA1, K_lds, KP_lds, qr, qpl, r32, hi); partialSM(pA0, pA1, m_reg, mnA, alA);
;   SLOAD(SO, KVBLK);
;   SWAIT(); SWRITE(1, SO); __syncthreads();
	ds_read_b128 v[6:9], v159 offset:32768
	ds_read_b128 v[10:13], v159 offset:40960
	s_waitcnt vmcnt(3) lgkmcnt(1)
	v_mfma_f32_32x32x16_bf16 v[16:31], v[6:9], v[108:111], 0
	v_or_b32_e32 v15, 32, v136
	v_bitop3_b32 v162, v15, v14, v225 bitop3:0xde
	v_bitop3_b32 v163, v78, v14, v225 bitop3:0xde
	v_bitop3_b32 v166, v79, v14, v225 bitop3:0xde
	s_mov_b32 s19, s29
	v_add_u32_e32 v177, v51, v83
	s_mov_b32 s78, 2
	s_waitcnt lgkmcnt(0)
	v_mfma_f32_32x32x16_bf16 v[32:47], v[10:13], v[108:111], 0
	ds_read_b128 v[6:9], v162 offset:32768
	ds_read_b128 v[10:13], v162 offset:40960
	v_add_u32_e32 v183, 0x12000, v84
	v_lshl_or_b32 v150, v148, 2, v139
	v_mov_b32_e32 v151, 0
	s_waitcnt vmcnt(2) lgkmcnt(1)
	v_mfma_f32_32x32x16_bf16 v[16:31], v[6:9], v[104:107], v[16:31]
	s_waitcnt lgkmcnt(0)
	v_mfma_f32_32x32x16_bf16 v[32:47], v[10:13], v[104:107], v[32:47]
	ds_read_b128 v[6:9], v163 offset:32768
	ds_read_b128 v[10:13], v163 offset:40960
	s_waitcnt vmcnt(1) lgkmcnt(1)
	v_mfma_f32_32x32x16_bf16 v[16:31], v[6:9], v[100:103], v[16:31]
	s_waitcnt lgkmcnt(0)
	v_mfma_f32_32x32x16_bf16 v[32:47], v[10:13], v[100:103], v[32:47]
	ds_read_b128 v[6:9], v166 offset:32768
	ds_read_b128 v[10:13], v166 offset:40960
	s_waitcnt vmcnt(0) lgkmcnt(1)
	v_mfma_f32_32x32x16_bf16 v[16:31], v[6:9], v[96:99], v[16:31]
	v_or_b32_e32 v6, 0x80, v136
	v_bitop3_b32 v167, v6, v14, v225 bitop3:0xde
	s_waitcnt lgkmcnt(0)
	v_mfma_f32_32x32x16_bf16 v[32:47], v[10:13], v[96:99], v[32:47]
	ds_read_b128 v[6:9], v167 offset:32768
	ds_read_b128 v[10:13], v77
	ds_read_b128 v[52:55], v167 offset:40960
	ds_read_b128 v[56:59], v77 offset:1024
	s_waitcnt lgkmcnt(2)
	v_mfma_f32_32x32x16_bf16 v[16:31], v[6:9], v[10:13], v[16:31]
	v_or_b32_e32 v6, 0xa0, v136
	v_bitop3_b32 v168, v6, v14, v225 bitop3:0xde
	s_waitcnt lgkmcnt(1)
	v_mfma_f32_32x32x16_bf16 v[32:47], v[52:55], v[10:13], v[32:47]
	ds_read_b128 v[6:9], v168 offset:32768
	ds_read_b128 v[10:13], v168 offset:40960
	s_waitcnt lgkmcnt(1)
	v_mfma_f32_32x32x16_bf16 v[16:31], v[6:9], v[56:59], v[16:31]
	v_or_b32_e32 v6, 0xc0, v136
	v_bitop3_b32 v160, v6, v14, v225 bitop3:0xde
	s_waitcnt lgkmcnt(0)
	v_mfma_f32_32x32x16_bf16 v[32:47], v[10:13], v[56:59], v[32:47]
	ds_read_b128 v[6:9], v160 offset:32768
	ds_read_b128 v[10:13], v77 offset:2048
	ds_read_b128 v[52:55], v160 offset:40960
	ds_read_b128 v[56:59], v77 offset:3072
	s_waitcnt lgkmcnt(2)
	v_mfma_f32_32x32x16_bf16 v[16:31], v[6:9], v[10:13], v[16:31]
	v_or_b32_e32 v6, 0xe0, v136
	v_bitop3_b32 v161, v6, v14, v225 bitop3:0xde
	v_lshlrev_b32_e32 v14, 7, v148
	v_bitop3_b32 v86, v136, v14, v85 bitop3:0xde
	v_or_b32_e32 v169, 0x10000, v86
	v_or_b32_e32 v170, 0x11000, v86
	v_bitop3_b32 v87, v15, v14, v85 bitop3:0xde
	s_waitcnt lgkmcnt(1)
	v_mfma_f32_32x32x16_bf16 v[32:47], v[52:55], v[10:13], v[32:47]
	ds_read_b128 v[6:9], v161 offset:32768
	ds_read_b128 v[10:13], v161 offset:40960
	v_or_b32_e32 v171, 0x10000, v87
	v_or_b32_e32 v172, 0x11000, v87
	v_bitop3_b32 v88, v78, v14, v85 bitop3:0xde
	v_or_b32_e32 v173, 0x10000, v88
	v_bitop3_b32 v175, v79, v14, v85 bitop3:0xde
	v_or_b32_e32 v174, 0x11000, v88
	s_waitcnt lgkmcnt(1)
	v_mfma_f32_32x32x16_bf16 v[16:31], v[6:9], v[56:59], v[16:31]
	v_or_b32_e32 v176, 0x10000, v175
	v_or_b32_e32 v178, 0x11000, v175
	v_or_b32_e32 v184, 0x12000, v86
	v_or_b32_e32 v185, 0x13000, v86
	v_or_b32_e32 v181, 0x12000, v87
	v_or_b32_e32 v182, 0x13000, v87
	v_or_b32_e32 v179, 0x12000, v88
	s_waitcnt lgkmcnt(0)
	v_mfma_f32_32x32x16_bf16 v[32:47], v[10:13], v[56:59], v[32:47]
	ds_read_b128 v[6:9], v169
	ds_read_b128 v[10:13], v77 offset:4096
	ds_read_b128 v[52:55], v170
	ds_read_b128 v[56:59], v77 offset:5120
	v_or_b32_e32 v180, 0x13000, v88
	s_waitcnt lgkmcnt(2)
	v_mfma_f32_32x32x16_bf16 v[16:31], v[6:9], v[10:13], v[16:31]
	ds_read_b128 v[6:9], v171
	s_waitcnt lgkmcnt(2)
	v_mfma_f32_32x32x16_bf16 v[32:47], v[52:55], v[10:13], v[32:47]
	v_lshl_add_u64 v[10:11], v[2:3], 0, s[4:5]
	s_mov_b64 s[4:5], 0xc0000
	v_lshl_add_u64 v[12:13], v[2:3], 0, s[4:5]
	global_load_dwordx4 v[52:55], v[10:11], off offset:256
	global_load_dwordx4 v[60:63], v[12:13], off offset:256
	v_add_co_u32_e32 v10, vcc, s73, v2
	v_mad_i64_i32 v[80:81], s[4:5], v76, s71, 0
	s_nop 0
	v_addc_co_u32_e32 v11, vcc, 0, v3, vcc
	v_add_co_u32_e32 v2, vcc, s74, v2
	s_waitcnt lgkmcnt(0)
	v_mfma_f32_32x32x16_bf16 v[16:31], v[6:9], v[56:59], v[16:31]
	v_addc_co_u32_e32 v3, vcc, 0, v3, vcc
	global_load_dwordx4 v[64:67], v[10:11], off
	global_load_dwordx4 v[68:71], v[2:3], off
	v_add_u32_e32 v2, 64, v76
	v_mad_i64_i32 v[2:3], s[4:5], v2, s71, v[4:5]
	v_lshl_add_u64 v[0:1], v[2:3], 0, v[0:1]
	global_load_dwordx4 v[72:75], v[0:1], off offset:2048
	v_lshlrev_b32_e32 v4, 3, v82
	v_and_b32_e32 v0, 0xc0, v83
	v_and_or_b32 v5, v4, 24, v0
	ds_read_b128 v[0:3], v172
	v_lshlrev_b32_e32 v6, 1, v50
	v_and_b32_e32 v6, 32, v6
	v_and_b32_e32 v4, 0x100, v4
	v_or3_b32 v153, v5, v6, v4
	ds_read_b128 v[4:7], v173
	s_waitcnt lgkmcnt(1)
	v_mfma_f32_32x32x16_bf16 v[32:47], v[0:3], v[56:59], v[32:47]
	ds_read_b128 v[0:3], v77 offset:6144
	ds_read_b128 v[8:11], v174
	ds_read_b128 v[56:59], v77 offset:7168
	ds_read_b128 v[76:79], v178
	s_mov_b32 s4, s29
	s_mov_b32 s5, s29
	v_or_b32_e32 v152, 0x4000, v153
	s_waitcnt lgkmcnt(3)
	v_mfma_f32_32x32x16_bf16 v[16:31], v[4:7], v[0:3], v[16:31]
	ds_read_b128 v[4:7], v176
	s_waitcnt vmcnt(0)
	s_waitcnt vmcnt(4)
	ds_write_b128 v154, v[52:55] offset:16384
	s_waitcnt vmcnt(3)
	ds_write_b128 v155, v[60:63] offset:16384
	v_mov_b32_e32 v238, v52
	v_mov_b32_e32 v239, v53
	v_mov_b32_e32 v240, v54
	v_mov_b32_e32 v241, v55
	v_mov_b32_e32 v242, v60
	v_mov_b32_e32 v243, v61
	v_mov_b32_e32 v244, v62
	v_mov_b32_e32 v245, v63
	s_waitcnt vmcnt(2)
	ds_write_b128 v156, v[64:67] offset:49152
	s_waitcnt vmcnt(1)
	ds_write_b128 v157, v[68:71] offset:49152
	s_waitcnt lgkmcnt(7)
	v_mfma_f32_32x32x16_bf16 v[32:47], v[8:11], v[0:3], v[32:47]
	s_waitcnt vmcnt(0)
	ds_write_b128 v183, v[72:75]
	s_waitcnt lgkmcnt(0)
	s_barrier
; DEV void partialSM(f32x16& p0, f32x16& p1, float& m_reg, float& mn, float& alpha) {
;   constexpr float C = SCALE * 1.4426950408889634f;
;   float pmax = p0[0];
; #pragma unroll
;   for (int r = 1; r < 16; ++r) pmax = fmaxf(pmax, p0[r]);
; #pragma unroll
;   for (int r = 0; r < 16; ++r) pmax = fmaxf(pmax, p1[r]);
;   { auto rr = __builtin_amdgcn_permlane32_swap(__float_as_uint(pmax), __float_as_uint(pmax), false, false);
;     pmax = fmaxf(__uint_as_float(rr[0]), __uint_as_float(rr[1])); }
;   if (__builtin_expect(__all(pmax - m_reg <= THR / SCALE), 1)) { mn = m_reg; alpha = 1.f; }
;   else { mn = fmaxf(m_reg, pmax); alpha = __builtin_amdgcn_exp2f((m_reg - mn) * C); m_reg = mn; }
;   float mnC = -mn * C;
; #pragma unroll
;   for (int r = 0; r < 16; ++r) p0[r] = fmaf(p0[r], C, mnC);
; #pragma unroll
;   for (int r = 0; r < 16; ++r) p1[r] = fmaf(p1[r], C, mnC);
; #pragma unroll
;   for (int r = 0; r < 16; ++r) p0[r] = __builtin_amdgcn_exp2f(p0[r]);
; }
; DEV void attn_item(const u16* __restrict__ Qb, const u16* __restrict__ Kh, const u16* __restrict__ Vh, const u16* __restrict__ KPh,
;                    u16* __restrict__ Ob, int seq, char* lds) {
;     ...
;   float m_reg = -1e30f, l_reg = 0; f32x16 o[4] = {}; bf16x8 qr[NQR];
	v_mfma_f32_32x32x16_bf16 v[16:31], v[4:7], v[56:59], v[16:31]
	v_mov_b64_e32 v[0:1], s[4:5]
	v_mov_b64_e32 v[2:3], s[6:7]
	v_mov_b64_e32 v[4:5], s[8:9]
	v_mov_b64_e32 v[6:7], s[10:11]
	v_mov_b64_e32 v[8:9], s[12:13]
	v_mov_b64_e32 v[10:11], s[14:15]
	v_mov_b64_e32 v[12:13], s[16:17]
	v_mfma_f32_32x32x16_bf16 v[32:47], v[76:79], v[56:59], v[32:47]
	s_nop 3
	v_max_f32_e32 v56, v17, v17
	v_max_f32_e32 v57, v16, v16
	v_max_f32_e32 v56, v57, v56
	v_max3_f32 v56, v56, v18, v19
	v_max3_f32 v56, v56, v20, v21
	v_max3_f32 v56, v56, v22, v23
	v_max3_f32 v56, v56, v24, v25
	v_max3_f32 v56, v56, v26, v27
	v_max3_f32 v56, v56, v28, v29
	v_max3_f32 v56, v56, v30, v31
	v_max3_f32 v56, v56, v32, v33
	v_max3_f32 v56, v56, v34, v35
	v_max3_f32 v56, v56, v36, v37
	v_max3_f32 v56, v56, v38, v39
	v_max3_f32 v56, v56, v40, v41
	v_max3_f32 v56, v56, v42, v43
	v_max3_f32 v56, v56, v44, v45
	v_max3_f32 v56, v56, v46, v47
	v_mov_b32_e32 v57, v56
	s_nop 1
	v_permlane32_swap_b32_e32 v56, v57
	v_max_f32_e32 v57, v57, v57
	v_max_f32_e32 v56, v56, v56
	v_max_f32_e32 v56, v56, v57
	v_add_f32_e32 v57, 0x7149f2ca, v56
	v_cmp_ge_f32_e32 vcc, s72, v57
	s_cmp_eq_u64 vcc, exec
	v_max_f32_e32 v53, 0xf149f2ca, v56
	s_cselect_b64 vcc, -1, 0
	v_cndmask_b32_e32 v132, v53, v146, vcc
	v_mul_f32_e32 v52, 0xbdd53b94, v132
	v_fmamk_f32 v16, v16, 0x3dd53b94, v52
	v_exp_f32_e32 v196, v16
	v_fmamk_f32 v16, v17, 0x3dd53b94, v52
	v_exp_f32_e32 v199, v16
	v_fmamk_f32 v16, v18, 0x3dd53b94, v52
	v_exp_f32_e32 v197, v16
	v_fmamk_f32 v16, v19, 0x3dd53b94, v52
	v_exp_f32_e32 v200, v16
	v_fmamk_f32 v16, v20, 0x3dd53b94, v52
	v_exp_f32_e32 v198, v16
	v_fmamk_f32 v16, v21, 0x3dd53b94, v52
	v_exp_f32_e32 v201, v16
	v_fmamk_f32 v16, v22, 0x3dd53b94, v52
	v_exp_f32_e32 v194, v16
	v_fmamk_f32 v16, v23, 0x3dd53b94, v52
	v_exp_f32_e32 v195, v16
	v_fmamk_f32 v16, v24, 0x3dd53b94, v52
	v_exp_f32_e32 v134, v16
	v_fmamk_f32 v16, v25, 0x3dd53b94, v52
	v_exp_f32_e32 v192, v16
	v_fmamk_f32 v16, v26, 0x3dd53b94, v52
	v_exp_f32_e32 v135, v16
	v_fmamk_f32 v16, v27, 0x3dd53b94, v52
	v_exp_f32_e32 v193, v16
	v_fmamk_f32 v16, v28, 0x3dd53b94, v52
	v_exp_f32_e32 v128, v16
	v_fmamk_f32 v16, v29, 0x3dd53b94, v52
	v_pk_fma_f32 v[116:117], v[38:39], s[30:31], v[52:53] op_sel_hi:[1,0,0]
	v_sub_f32_e32 v38, 0xf149f2ca, v53
	v_exp_f32_e32 v130, v16
	v_fmamk_f32 v16, v30, 0x3dd53b94, v52
	v_mov_b64_e32 v[14:15], s[18:19]
	v_mul_f32_e32 v38, 0x3dd53b94, v38
	v_exp_f32_e32 v129, v16
	v_mad_u64_u32 v[16:17], s[4:5], s54, v147, v[80:81]
	v_and_b32_e32 v18, 7, v50
	v_exp_f32_e32 v38, v38
	v_add_u32_e32 v17, s0, v17
	v_lshl_or_b32 v16, v18, 4, v16
	v_pk_fma_f32 v[114:115], v[46:47], s[30:31], v[52:53] op_sel_hi:[1,0,0]
	v_pk_fma_f32 v[118:119], v[44:45], s[30:31], v[52:53] op_sel_hi:[1,0,0]
	v_pk_fma_f32 v[122:123], v[42:43], s[30:31], v[52:53] op_sel_hi:[1,0,0]
	v_pk_fma_f32 v[112:113], v[40:41], s[30:31], v[52:53] op_sel_hi:[1,0,0]
	v_pk_fma_f32 v[120:121], v[36:37], s[30:31], v[52:53] op_sel_hi:[1,0,0]
	v_pk_fma_f32 v[124:125], v[34:35], s[30:31], v[52:53] op_sel_hi:[1,0,0]
	v_pk_fma_f32 v[126:127], v[32:33], s[30:31], v[52:53] op_sel_hi:[1,0,0]
	v_fmac_f32_e32 v52, 0x3dd53b94, v31
	v_lshl_add_u64 v[140:141], s[26:27], 0, v[16:17]
	v_lshl_add_u64 v[16:17], s[54:55], 0, v[48:49]
	v_exp_f32_e32 v131, v52
	v_lshlrev_b64 v[16:17], 13, v[16:17]
	v_and_b32_e32 v18, 15, v50
	s_add_u32 s0, s31, s62
	v_lshl_or_b32 v16, v18, 4, v16
	s_addc_u32 s1, s70, s63
	v_cndmask_b32_e64 v186, v38, 1.0, vcc
	v_lshl_add_u64 v[142:143], s[0:1], 0, v[16:17]
	v_mov_b64_e32 v[62:63], v[14:15]
	v_mov_b64_e32 v[46:47], v[14:15]
	v_mov_b64_e32 v[30:31], v[14:15]
	v_cmp_gt_u32_e64 s[6:7], 32, v82
	v_mov_b64_e32 v[60:61], v[12:13]
	v_mov_b64_e32 v[58:59], v[10:11]
	v_mov_b64_e32 v[56:57], v[8:9]
	v_mov_b64_e32 v[54:55], v[6:7]
	v_mov_b64_e32 v[52:53], v[4:5]
	v_mov_b64_e32 v[50:51], v[2:3]
	v_mov_b64_e32 v[48:49], v[0:1]
	v_mov_b64_e32 v[44:45], v[12:13]
	v_mov_b64_e32 v[42:43], v[10:11]
	v_mov_b64_e32 v[40:41], v[8:9]
	v_mov_b64_e32 v[38:39], v[6:7]
	v_mov_b64_e32 v[36:37], v[4:5]
	v_mov_b64_e32 v[34:35], v[2:3]
	v_mov_b64_e32 v[32:33], v[0:1]
	v_mov_b64_e32 v[28:29], v[12:13]
	v_mov_b64_e32 v[26:27], v[10:11]
	v_mov_b64_e32 v[24:25], v[8:9]
	v_mov_b64_e32 v[22:23], v[6:7]
	v_mov_b64_e32 v[20:21], v[4:5]
	v_mov_b64_e32 v[18:19], v[2:3]
	v_mov_b64_e32 v[16:17], v[0:1]
	.p2align 6
